# adds peeled first K-iteration with C=0 (no accumulator zeroing) to the other two GEMM loops
# baseline (speedup 1.0000x reference)
; #define PG8_STAGE(bufoff, gbase, voff) do { _Pragma("unroll") for (int _i = 0; _i < 2; ++_i) \
;         __builtin_amdgcn_global_load_lds((const unsigned*)((const char*)(gbase) + (voff)[_i]), (PG8_LAS unsigned*)(lds + (bufoff) + ldsw + _i * 8192), 16, 0, 0); } while (0)
; #define PG8_LDA(dst, b, h) do { _Pragma("unroll") for (int m = 0; m < 4; ++m) _Pragma("unroll") for (int k = 0; k < 2; ++k) dst[m][k] = *(const PG8_LAS bf16x8*)(lds + PG8_SA(b, h) + aoff + m * 2048 + k * 1024); } while (0)
; #define PG8_LDB(dst, b, h) do { _Pragma("unroll") for (int n = 0; n < 2; ++n) _Pragma("unroll") for (int k = 0; k < 2; ++k) dst[n][k] = *(const PG8_LAS bf16x8*)(lds + PG8_SB(b, h) + boff + n * 2048 + k * 1024); } while (0)
; #define PG8_WAIT_V(n) asm volatile("s_waitcnt vmcnt(" #n ")" ::: "memory")
; #define PG8_BAR __builtin_amdgcn_s_barrier()
; template <class Epi, class Sched, bool ALIGN_EPI = false, bool SP2 = false>
; __device__ __forceinline__ void gemm_phase(PG8_LAS unsigned char* lds, const Gemm g, const Sched& S, const Epi& E) {
;     ...
;     f32x4 acc[2][2][4][2];
; #pragma unroll
;     for (int a = 0; a < 2; ++a)
; #pragma unroll
;         for (int b = 0; b < 2; ++b)
; #pragma unroll
;             for (int m = 0; m < 4; ++m)
; #pragma unroll
;                 for (int n = 0; n < 2; ++n) acc[a][b][m][n] = (f32x4){0.f, 0.f, 0.f, 0.f};
;     ...
;             PG8_LDB(B0, 0, 0); PG8_LDB(B1, 0, 1); PG8_SCHED; PG8_LDA(At, 0, 0); PG8_STAGE(PG8_SA(1, 1), a1 + hstepA, voffA);
;             PG8_WAIT_V(8); PG8_WAIT_L(0); PG8_BAR; PG8_MMA(0, 0, At, B0); PG8_MMA(0, 1, At, B1); PG8_BAR; PG8_SCHED;
;             PG8_LDA(At, 0, 1); PG8_STAGE(PG8_SB(0, 0), b2, voffB); PG8_STAGE(PG8_SB(0, 1), b2 + hstepB, voffB); PG8_STAGE(PG8_SA(0, 0), a2, voffA);
;             PG8_WAIT_V(8); PG8_WAIT_L(0); PG8_BAR; PG8_MMA(1, 0, At, B0); PG8_MMA(1, 1, At, B1); PG8_BAR; PG8_SCHED;
;             PG8_LDB(B0, 1, 0); PG8_LDB(B1, 1, 1); PG8_SCHED; PG8_LDA(At, 1, 0); PG8_STAGE(PG8_SA(0, 1), a2 + hstepA, voffA);
;             PG8_WAIT_V(8); PG8_WAIT_L(0); PG8_BAR; PG8_MMA(0, 0, At, B0); PG8_MMA(0, 1, At, B1); PG8_BAR; PG8_SCHED;
;             PG8_LDA(At, 1, 1); PG8_STAGE(PG8_SB(1, 0), b3, voffB); PG8_STAGE(PG8_SB(1, 1), b3 + hstepB, voffB); PG8_STAGE(PG8_SA(1, 0), a3, voffA);
;             PG8_WAIT_V(8); PG8_WAIT_L(0); PG8_BAR; PG8_MMA(1, 0, At, B0); PG8_MMA(1, 1, At, B1); PG8_BAR; PG8_SCHED;
.LBB0_236:
	s_ashr_i32 s89, s88, 31
	s_lshl_b64 s[50:51], s[88:89], 19
	s_add_u32 s90, s56, s50
	s_addc_u32 s91, s57, s51
	s_and_b64 s[50:51], s[10:11], exec
	s_cselect_b32 s15, s91, s95
	s_cselect_b32 s34, s90, s94
	s_ashr_i32 s87, s86, 31
	s_lshl_b64 s[50:51], s[86:87], 19
	s_add_u32 s92, s20, s50
	s_addc_u32 s93, s21, s51
	s_and_b64 s[50:51], s[10:11], exec
	s_cselect_b32 s87, s93, s13
	s_cselect_b32 s89, s92, s12
	s_add_u32 vcc_lo, s12, 0x100
	s_addc_u32 vcc_hi, s13, 0
	s_add_u32 s12, s94, 0x40080
	s_addc_u32 s13, s95, 0
	s_mov_b32 s50, -2
	s_waitcnt lgkmcnt(0)
	s_add_u32 s51, s12, 0xfffc0080
	s_addc_u32 s80, s13, -1
	s_add_i32 s81, 0, 0x10000
	s_cmp_eq_u32 s50, 12
	s_cselect_b32 s97, s15, s80
	s_cselect_b32 s96, s34, s51
	s_cselect_b32 s95, s87, vcc_hi
	s_cselect_b32 s94, s89, vcc_lo
	s_add_i32 s51, 0, 0x14000
	v_add_u32_e32 v44, s81, v164
	v_add_u32_e32 v160, s51, v164
	ds_read_b128 v[24:27], v44
	ds_read_b128 v[28:31], v44 offset:1024
	ds_read_b128 v[40:43], v44 offset:2048
	ds_read_b128 v[44:47], v44 offset:3072
	ds_read_b128 v[156:159], v160
	ds_read_b128 v[188:191], v160 offset:1024
	ds_read_b128 v[192:195], v160 offset:2048
	ds_read_b128 v[196:199], v160 offset:3072
	v_lshl_add_u64 v[160:161], s[12:13], 0, v[154:155]
	s_add_i32 m0, s5, 0xc000
	ds_read_b128 v[200:203], v168
	ds_read_b128 v[204:207], v168 offset:1024
	ds_read_b128 v[208:211], v168 offset:2048
	ds_read_b128 v[212:215], v168 offset:3072
	ds_read_b128 v[216:219], v168 offset:4096
	ds_read_b128 v[220:223], v168 offset:5120
	ds_read_b128 v[224:227], v168 offset:6144
	ds_read_b128 v[228:231], v168 offset:7168
	global_load_lds_dwordx4 v[160:161], off
	v_lshl_add_u64 v[160:161], s[12:13], 0, v[152:153]
	s_add_i32 m0, s5, 0xe000
	s_nop 0
	global_load_lds_dwordx4 v[160:161], off
	s_waitcnt vmcnt(8)
	s_waitcnt lgkmcnt(0)
	s_barrier
	s_setprio 1
	s_waitcnt lgkmcnt(0)
	v_mfma_f32_16x16x32_bf16 v[140:143], v[24:27], v[200:203], 0
	v_mfma_f32_16x16x32_bf16 v[136:139], v[40:43], v[200:203], 0
	v_mfma_f32_16x16x32_bf16 v[124:127], v[24:27], v[208:211], 0
	v_mfma_f32_16x16x32_bf16 v[120:123], v[40:43], v[208:211], 0
	v_mfma_f32_16x16x32_bf16 v[108:111], v[24:27], v[216:219], 0
	v_mfma_f32_16x16x32_bf16 v[104:107], v[40:43], v[216:219], 0
	v_mfma_f32_16x16x32_bf16 v[92:95], v[24:27], v[224:227], 0
	v_mfma_f32_16x16x32_bf16 v[88:91], v[40:43], v[224:227], 0
	v_mfma_f32_16x16x32_bf16 v[140:143], v[28:31], v[204:207], v[140:143]
	v_mfma_f32_16x16x32_bf16 v[136:139], v[44:47], v[204:207], v[136:139]
	v_mfma_f32_16x16x32_bf16 v[124:127], v[28:31], v[212:215], v[124:127]
	v_mfma_f32_16x16x32_bf16 v[120:123], v[44:47], v[212:215], v[120:123]
	v_mfma_f32_16x16x32_bf16 v[108:111], v[28:31], v[220:223], v[108:111]
	v_mfma_f32_16x16x32_bf16 v[104:107], v[44:47], v[220:223], v[104:107]
	v_mfma_f32_16x16x32_bf16 v[92:95], v[28:31], v[228:231], v[92:95]
	v_mfma_f32_16x16x32_bf16 v[88:91], v[44:47], v[228:231], v[88:91]
	s_setprio 0
	s_setprio 1
	v_mfma_f32_16x16x32_bf16 v[132:135], v[156:159], v[200:203], 0
	v_mfma_f32_16x16x32_bf16 v[128:131], v[192:195], v[200:203], 0
	v_mfma_f32_16x16x32_bf16 v[116:119], v[156:159], v[208:211], 0
	v_mfma_f32_16x16x32_bf16 v[112:115], v[192:195], v[208:211], 0
	v_mfma_f32_16x16x32_bf16 v[100:103], v[156:159], v[216:219], 0
	v_mfma_f32_16x16x32_bf16 v[96:99], v[192:195], v[216:219], 0
	v_mfma_f32_16x16x32_bf16 v[84:87], v[156:159], v[224:227], 0
	v_mfma_f32_16x16x32_bf16 v[80:83], v[192:195], v[224:227], 0
	v_mfma_f32_16x16x32_bf16 v[132:135], v[188:191], v[204:207], v[132:135]
	v_mfma_f32_16x16x32_bf16 v[128:131], v[196:199], v[204:207], v[128:131]
	v_mfma_f32_16x16x32_bf16 v[116:119], v[188:191], v[212:215], v[116:119]
	v_mfma_f32_16x16x32_bf16 v[112:115], v[196:199], v[212:215], v[112:115]
	v_mfma_f32_16x16x32_bf16 v[100:103], v[188:191], v[220:223], v[100:103]
	v_mfma_f32_16x16x32_bf16 v[96:99], v[196:199], v[220:223], v[96:99]
	v_mfma_f32_16x16x32_bf16 v[84:87], v[188:191], v[228:231], v[84:87]
	v_mfma_f32_16x16x32_bf16 v[80:83], v[196:199], v[228:231], v[80:83]
	s_setprio 0
	s_barrier
	s_add_i32 s80, s81, s4
	v_lshl_add_u64 v[160:161], s[94:95], 0, v[144:145]
	s_mov_b32 m0, s80
	ds_read_b128 v[200:203], v168 offset:16384
	ds_read_b128 v[204:207], v168 offset:17408
	ds_read_b128 v[208:211], v168 offset:18432
	ds_read_b128 v[212:215], v168 offset:19456
	ds_read_b128 v[216:219], v168 offset:20480
	ds_read_b128 v[220:223], v168 offset:21504
	ds_read_b128 v[224:227], v168 offset:22528
	ds_read_b128 v[228:231], v168 offset:23552
	global_load_lds_dwordx4 v[160:161], off
	s_add_i32 m0, s80, 0x2000
	s_add_u32 s80, s94, 0x40000
	v_lshl_add_u64 v[174:175], s[94:95], 0, v[150:151]
	s_addc_u32 s81, s95, 0
	s_add_i32 s51, s51, s4
	global_load_lds_dwordx4 v[174:175], off
	v_lshl_add_u64 v[232:233], s[80:81], 0, v[144:145]
	s_mov_b32 m0, s51
	v_lshl_add_u64 v[234:235], s[96:97], 0, v[148:149]
	global_load_lds_dwordx4 v[232:233], off
	v_lshl_add_u64 v[232:233], s[80:81], 0, v[150:151]
	s_add_i32 m0, s51, 0x2000
	s_nop 0
	global_load_lds_dwordx4 v[232:233], off
	v_lshl_add_u64 v[232:233], s[96:97], 0, v[146:147]
	s_mov_b32 m0, s5
	s_nop 0
	global_load_lds_dwordx4 v[232:233], off
	s_mov_b32 m0, s79
	s_nop 0
	global_load_lds_dwordx4 v[234:235], off
	s_waitcnt vmcnt(8)
	s_waitcnt lgkmcnt(0)
	s_barrier
; #define PG8_STAGE(bufoff, gbase, voff) do { _Pragma("unroll") for (int _i = 0; _i < 2; ++_i) \
;         __builtin_amdgcn_global_load_lds((const unsigned*)((const char*)(gbase) + (voff)[_i]), (PG8_LAS unsigned*)(lds + (bufoff) + ldsw + _i * 8192), 16, 0, 0); } while (0)
; #define PG8_LDA(dst, b, h) do { _Pragma("unroll") for (int m = 0; m < 4; ++m) _Pragma("unroll") for (int k = 0; k < 2; ++k) dst[m][k] = *(const PG8_LAS bf16x8*)(lds + PG8_SA(b, h) + aoff + m * 2048 + k * 1024); } while (0)
; #define PG8_LDB(dst, b, h) do { _Pragma("unroll") for (int n = 0; n < 2; ++n) _Pragma("unroll") for (int k = 0; k < 2; ++k) dst[n][k] = *(const PG8_LAS bf16x8*)(lds + PG8_SB(b, h) + boff + n * 2048 + k * 1024); } while (0)
; #define PG8_MMA(ai, bj, At, Bt) do { __builtin_amdgcn_s_setprio(1); _Pragma("unroll") for (int m = 0; m < 4; ++m) _Pragma("unroll") for (int n = 0; n < 2; ++n) _Pragma("unroll") for (int k = 0; k < 2; ++k) \
;         acc[ai][bj][m][n] = __builtin_amdgcn_mfma_f32_16x16x32_bf16(Bt[n][k], At[m][k], acc[ai][bj][m][n], 0, 0, 0); __builtin_amdgcn_s_setprio(0); } while (0)
; #define PG8_WAIT_V(n) asm volatile("s_waitcnt vmcnt(" #n ")" ::: "memory")
; #define PG8_WAIT_L(n) asm volatile("s_waitcnt lgkmcnt(" #n ")" ::: "memory")
; #define PG8_BAR __builtin_amdgcn_s_barrier()
; #define PG8_SCHED __builtin_amdgcn_sched_barrier(0)
; template <class Epi, class Sched, bool ALIGN_EPI = false, bool SP2 = false>
; __device__ __forceinline__ void gemm_phase(PG8_LAS unsigned char* lds, const Gemm g, const Sched& S, const Epi& E) {
;     ...
;             PG8_LDA(At, 0, 1); PG8_STAGE(PG8_SB(0, 0), b2, voffB); PG8_STAGE(PG8_SB(0, 1), b2 + hstepB, voffB); PG8_STAGE(PG8_SA(0, 0), a2, voffA);
;             PG8_WAIT_V(8); PG8_WAIT_L(0); PG8_BAR; PG8_MMA(1, 0, At, B0); PG8_MMA(1, 1, At, B1); PG8_BAR; PG8_SCHED;
;             PG8_LDB(B0, 1, 0); PG8_LDB(B1, 1, 1); PG8_SCHED; PG8_LDA(At, 1, 0); PG8_STAGE(PG8_SA(0, 1), a2 + hstepA, voffA);
;             PG8_WAIT_V(8); PG8_WAIT_L(0); PG8_BAR; PG8_MMA(0, 0, At, B0); PG8_MMA(0, 1, At, B1); PG8_BAR; PG8_SCHED;
	s_setprio 1
	s_waitcnt lgkmcnt(0)
	v_mfma_f32_16x16x32_bf16 v[76:79], v[24:27], v[200:203], 0
	v_mfma_f32_16x16x32_bf16 v[72:75], v[40:43], v[200:203], 0
	v_mfma_f32_16x16x32_bf16 v[60:63], v[24:27], v[208:211], 0
	v_mfma_f32_16x16x32_bf16 v[56:59], v[40:43], v[208:211], 0
	v_mfma_f32_16x16x32_bf16 v[36:39], v[24:27], v[216:219], 0
	v_mfma_f32_16x16x32_bf16 v[32:35], v[40:43], v[216:219], 0
	v_mfma_f32_16x16x32_bf16 v[12:15], v[24:27], v[224:227], 0
	v_mfma_f32_16x16x32_bf16 v[8:11], v[40:43], v[224:227], 0
	v_mfma_f32_16x16x32_bf16 v[76:79], v[28:31], v[204:207], v[76:79]
	v_mfma_f32_16x16x32_bf16 v[72:75], v[44:47], v[204:207], v[72:75]
	v_mfma_f32_16x16x32_bf16 v[60:63], v[28:31], v[212:215], v[60:63]
	v_mfma_f32_16x16x32_bf16 v[56:59], v[44:47], v[212:215], v[56:59]
	v_mfma_f32_16x16x32_bf16 v[36:39], v[28:31], v[220:223], v[36:39]
	v_mfma_f32_16x16x32_bf16 v[32:35], v[44:47], v[220:223], v[32:35]
	v_mfma_f32_16x16x32_bf16 v[12:15], v[28:31], v[228:231], v[12:15]
	v_mfma_f32_16x16x32_bf16 v[8:11], v[44:47], v[228:231], v[8:11]
	s_setprio 0
	s_setprio 1
	v_mfma_f32_16x16x32_bf16 v[20:23], v[156:159], v[216:219], 0
	v_mfma_f32_16x16x32_bf16 v[16:19], v[192:195], v[216:219], 0
	v_mfma_f32_16x16x32_bf16 v[4:7], v[156:159], v[224:227], 0
	v_mfma_f32_16x16x32_bf16 v[0:3], v[192:195], v[224:227], 0
	v_mfma_f32_16x16x32_bf16 v[24:27], v[156:159], v[200:203], 0
	v_mfma_f32_16x16x32_bf16 v[28:31], v[192:195], v[200:203], 0
	v_mfma_f32_16x16x32_bf16 v[40:43], v[156:159], v[208:211], 0
	v_mfma_f32_16x16x32_bf16 v[44:47], v[192:195], v[208:211], 0
	v_mfma_f32_16x16x32_bf16 v[20:23], v[188:191], v[220:223], v[20:23]
	v_mfma_f32_16x16x32_bf16 v[16:19], v[196:199], v[220:223], v[16:19]
	v_mfma_f32_16x16x32_bf16 v[4:7], v[188:191], v[228:231], v[4:7]
	v_mfma_f32_16x16x32_bf16 v[0:3], v[196:199], v[228:231], v[0:3]
	v_mfma_f32_16x16x32_bf16 v[24:27], v[188:191], v[204:207], v[24:27]
	v_mfma_f32_16x16x32_bf16 v[28:31], v[196:199], v[204:207], v[28:31]
	v_mfma_f32_16x16x32_bf16 v[40:43], v[188:191], v[212:215], v[40:43]
	v_mfma_f32_16x16x32_bf16 v[44:47], v[196:199], v[212:215], v[44:47]
	s_setprio 0
	s_barrier
	s_add_i32 s51, 0, 0x18000
	s_add_i32 s69, 0, 0x1c000
	v_add_u32_e32 v68, s51, v164
	v_add_u32_e32 v169, s69, v164
	ds_read_b128 v[48:51], v68
	ds_read_b128 v[52:55], v68 offset:1024
	ds_read_b128 v[64:67], v68 offset:2048
	ds_read_b128 v[68:71], v68 offset:3072
	ds_read_b128 v[156:159], v169
	ds_read_b128 v[188:191], v169 offset:1024
	ds_read_b128 v[192:195], v169 offset:2048
	ds_read_b128 v[196:199], v169 offset:3072
	s_add_u32 s80, s96, 0x40000
	s_addc_u32 s81, s97, 0
	s_mov_b32 m0, s72
	v_lshl_add_u64 v[236:237], s[80:81], 0, v[146:147]
	ds_read_b128 v[200:203], v168 offset:32768
	ds_read_b128 v[204:207], v168 offset:33792
	ds_read_b128 v[208:211], v168 offset:34816
	ds_read_b128 v[212:215], v168 offset:35840
	ds_read_b128 v[216:219], v168 offset:36864
	ds_read_b128 v[220:223], v168 offset:37888
	ds_read_b128 v[224:227], v168 offset:38912
	ds_read_b128 v[228:231], v168 offset:39936
	global_load_lds_dwordx4 v[236:237], off
	v_lshl_add_u64 v[236:237], s[80:81], 0, v[148:149]
	s_mov_b32 m0, s73
	s_nop 0
	global_load_lds_dwordx4 v[236:237], off
	s_waitcnt vmcnt(8)
	s_waitcnt lgkmcnt(0)
	s_barrier
	s_setprio 1
	s_waitcnt lgkmcnt(0)
	v_mfma_f32_16x16x32_bf16 v[140:143], v[48:51], v[200:203], v[140:143]
	v_mfma_f32_16x16x32_bf16 v[136:139], v[64:67], v[200:203], v[136:139]
	v_mfma_f32_16x16x32_bf16 v[124:127], v[48:51], v[208:211], v[124:127]
	v_mfma_f32_16x16x32_bf16 v[120:123], v[64:67], v[208:211], v[120:123]
	v_mfma_f32_16x16x32_bf16 v[108:111], v[48:51], v[216:219], v[108:111]
	v_mfma_f32_16x16x32_bf16 v[104:107], v[64:67], v[216:219], v[104:107]
	v_mfma_f32_16x16x32_bf16 v[92:95], v[48:51], v[224:227], v[92:95]
	v_mfma_f32_16x16x32_bf16 v[88:91], v[64:67], v[224:227], v[88:91]
	v_mfma_f32_16x16x32_bf16 v[140:143], v[52:55], v[204:207], v[140:143]
	v_mfma_f32_16x16x32_bf16 v[136:139], v[68:71], v[204:207], v[136:139]
	v_mfma_f32_16x16x32_bf16 v[124:127], v[52:55], v[212:215], v[124:127]
	v_mfma_f32_16x16x32_bf16 v[120:123], v[68:71], v[212:215], v[120:123]
	v_mfma_f32_16x16x32_bf16 v[108:111], v[52:55], v[220:223], v[108:111]
	v_mfma_f32_16x16x32_bf16 v[104:107], v[68:71], v[220:223], v[104:107]
	v_mfma_f32_16x16x32_bf16 v[92:95], v[52:55], v[228:231], v[92:95]
	v_mfma_f32_16x16x32_bf16 v[88:91], v[68:71], v[228:231], v[88:91]
	s_setprio 0
	s_setprio 1
	v_mfma_f32_16x16x32_bf16 v[132:135], v[156:159], v[200:203], v[132:135]
	v_mfma_f32_16x16x32_bf16 v[128:131], v[192:195], v[200:203], v[128:131]
	v_mfma_f32_16x16x32_bf16 v[116:119], v[156:159], v[208:211], v[116:119]
	v_mfma_f32_16x16x32_bf16 v[112:115], v[192:195], v[208:211], v[112:115]
	v_mfma_f32_16x16x32_bf16 v[100:103], v[156:159], v[216:219], v[100:103]
	v_mfma_f32_16x16x32_bf16 v[96:99], v[192:195], v[216:219], v[96:99]
	v_mfma_f32_16x16x32_bf16 v[84:87], v[156:159], v[224:227], v[84:87]
	v_mfma_f32_16x16x32_bf16 v[80:83], v[192:195], v[224:227], v[80:83]
	v_mfma_f32_16x16x32_bf16 v[132:135], v[188:191], v[204:207], v[132:135]
	v_mfma_f32_16x16x32_bf16 v[128:131], v[196:199], v[204:207], v[128:131]
	v_mfma_f32_16x16x32_bf16 v[116:119], v[188:191], v[212:215], v[116:119]
	v_mfma_f32_16x16x32_bf16 v[112:115], v[196:199], v[212:215], v[112:115]
	v_mfma_f32_16x16x32_bf16 v[100:103], v[188:191], v[220:223], v[100:103]
	v_mfma_f32_16x16x32_bf16 v[96:99], v[196:199], v[220:223], v[96:99]
	v_mfma_f32_16x16x32_bf16 v[84:87], v[188:191], v[228:231], v[84:87]
	v_mfma_f32_16x16x32_bf16 v[80:83], v[196:199], v[228:231], v[80:83]
	s_setprio 0
	s_barrier
; #define PG8_STAGE(bufoff, gbase, voff) do { _Pragma("unroll") for (int _i = 0; _i < 2; ++_i) \
;         __builtin_amdgcn_global_load_lds((const unsigned*)((const char*)(gbase) + (voff)[_i]), (PG8_LAS unsigned*)(lds + (bufoff) + ldsw + _i * 8192), 16, 0, 0); } while (0)
; #define PG8_LDA(dst, b, h) do { _Pragma("unroll") for (int m = 0; m < 4; ++m) _Pragma("unroll") for (int k = 0; k < 2; ++k) dst[m][k] = *(const PG8_LAS bf16x8*)(lds + PG8_SA(b, h) + aoff + m * 2048 + k * 1024); } while (0)
; #define PG8_MMA(ai, bj, At, Bt) do { __builtin_amdgcn_s_setprio(1); _Pragma("unroll") for (int m = 0; m < 4; ++m) _Pragma("unroll") for (int n = 0; n < 2; ++n) _Pragma("unroll") for (int k = 0; k < 2; ++k) \
;         acc[ai][bj][m][n] = __builtin_amdgcn_mfma_f32_16x16x32_bf16(Bt[n][k], At[m][k], acc[ai][bj][m][n], 0, 0, 0); __builtin_amdgcn_s_setprio(0); } while (0)
; #define PG8_WAIT_V(n) asm volatile("s_waitcnt vmcnt(" #n ")" ::: "memory")
; #define PG8_WAIT_L(n) asm volatile("s_waitcnt lgkmcnt(" #n ")" ::: "memory")
; #define PG8_BAR __builtin_amdgcn_s_barrier()
; #define PG8_SCHED __builtin_amdgcn_sched_barrier(0)
; template <class Epi, class Sched, bool ALIGN_EPI = false, bool SP2 = false>
; __device__ __forceinline__ void gemm_phase(PG8_LAS unsigned char* lds, const Gemm g, const Sched& S, const Epi& E) {
;     ...
;         for (int t = 0; t < nt; t += 2) {
;             const bool last = (t == nt - 2);
;             const char* a1 = cA + (size_t)(t + 1) * kstep;
;             const char* a2 = last ? nA : cA + (size_t)(t + 2) * kstep; const char* b2 = last ? nB : cB + (size_t)(t + 2) * kstep;
;             const char* a3 = a2 + kstep; const char* b3 = b2 + kstep;
;     ...
;             PG8_LDA(At, 1, 1); PG8_STAGE(PG8_SB(1, 0), b3, voffB); PG8_STAGE(PG8_SB(1, 1), b3 + hstepB, voffB); PG8_STAGE(PG8_SA(1, 0), a3, voffA);
;             PG8_WAIT_V(8); PG8_WAIT_L(0); PG8_BAR; PG8_MMA(1, 0, At, B0); PG8_MMA(1, 1, At, B1); PG8_BAR; PG8_SCHED;
	s_add_i32 s51, s51, s4
	v_lshl_add_u64 v[160:161], v[160:161], 0, s[48:49]
	s_mov_b32 m0, s51
	ds_read_b128 v[200:203], v168 offset:49152
	ds_read_b128 v[204:207], v168 offset:50176
	ds_read_b128 v[208:211], v168 offset:51200
	ds_read_b128 v[212:215], v168 offset:52224
	ds_read_b128 v[216:219], v168 offset:53248
	ds_read_b128 v[220:223], v168 offset:54272
	ds_read_b128 v[224:227], v168 offset:55296
	ds_read_b128 v[228:231], v168 offset:56320
	global_load_lds_dwordx4 v[160:161], off
	s_add_i32 m0, s51, 0x2000
	s_add_u32 s80, s94, 0x40080
	v_lshl_add_u64 v[160:161], v[174:175], 0, s[48:49]
	s_addc_u32 s81, s95, 0
	s_add_i32 s51, s69, s4
	global_load_lds_dwordx4 v[160:161], off
	v_lshl_add_u64 v[160:161], s[80:81], 0, v[144:145]
	s_mov_b32 m0, s51
	s_nop 0
	global_load_lds_dwordx4 v[160:161], off
	v_lshl_add_u64 v[160:161], s[80:81], 0, v[150:151]
	s_add_i32 m0, s51, 0x2000
	s_nop 0
	global_load_lds_dwordx4 v[160:161], off
	v_lshl_add_u64 v[160:161], v[232:233], 0, s[48:49]
	s_mov_b32 m0, s6
	s_nop 0
	global_load_lds_dwordx4 v[160:161], off
	v_lshl_add_u64 v[160:161], v[234:235], 0, s[48:49]
	s_mov_b32 m0, s7
	s_nop 0
	global_load_lds_dwordx4 v[160:161], off
	s_waitcnt vmcnt(8)
	s_waitcnt lgkmcnt(0)
	s_barrier
	s_setprio 1
	s_waitcnt lgkmcnt(0)
	v_mfma_f32_16x16x32_bf16 v[76:79], v[48:51], v[200:203], v[76:79]
	v_mfma_f32_16x16x32_bf16 v[72:75], v[64:67], v[200:203], v[72:75]
	v_mfma_f32_16x16x32_bf16 v[60:63], v[48:51], v[208:211], v[60:63]
	v_mfma_f32_16x16x32_bf16 v[56:59], v[64:67], v[208:211], v[56:59]
	v_mfma_f32_16x16x32_bf16 v[36:39], v[48:51], v[216:219], v[36:39]
	v_mfma_f32_16x16x32_bf16 v[32:35], v[64:67], v[216:219], v[32:35]
	v_mfma_f32_16x16x32_bf16 v[12:15], v[48:51], v[224:227], v[12:15]
	v_mfma_f32_16x16x32_bf16 v[8:11], v[64:67], v[224:227], v[8:11]
	v_mfma_f32_16x16x32_bf16 v[76:79], v[52:55], v[204:207], v[76:79]
	v_mfma_f32_16x16x32_bf16 v[72:75], v[68:71], v[204:207], v[72:75]
	v_mfma_f32_16x16x32_bf16 v[60:63], v[52:55], v[212:215], v[60:63]
	v_mfma_f32_16x16x32_bf16 v[56:59], v[68:71], v[212:215], v[56:59]
	v_mfma_f32_16x16x32_bf16 v[36:39], v[52:55], v[220:223], v[36:39]
	v_mfma_f32_16x16x32_bf16 v[32:35], v[68:71], v[220:223], v[32:35]
	v_mfma_f32_16x16x32_bf16 v[12:15], v[52:55], v[228:231], v[12:15]
	v_mfma_f32_16x16x32_bf16 v[8:11], v[68:71], v[228:231], v[8:11]
	s_setprio 0
	s_setprio 1
	v_mfma_f32_16x16x32_bf16 v[24:27], v[156:159], v[200:203], v[24:27]
	v_mfma_f32_16x16x32_bf16 v[68:71], v[188:191], v[204:207], v[24:27]
	v_mfma_f32_16x16x32_bf16 v[24:27], v[192:195], v[200:203], v[28:31]
	v_mfma_f32_16x16x32_bf16 v[64:67], v[196:199], v[204:207], v[24:27]
	v_mfma_f32_16x16x32_bf16 v[24:27], v[156:159], v[208:211], v[40:43]
	v_mfma_f32_16x16x32_bf16 v[52:55], v[188:191], v[212:215], v[24:27]
	v_mfma_f32_16x16x32_bf16 v[24:27], v[192:195], v[208:211], v[44:47]
	v_mfma_f32_16x16x32_bf16 v[20:23], v[156:159], v[216:219], v[20:23]
	v_mfma_f32_16x16x32_bf16 v[16:19], v[192:195], v[216:219], v[16:19]
	v_mfma_f32_16x16x32_bf16 v[4:7], v[156:159], v[224:227], v[4:7]
	v_mfma_f32_16x16x32_bf16 v[0:3], v[192:195], v[224:227], v[0:3]
	v_mfma_f32_16x16x32_bf16 v[48:51], v[196:199], v[212:215], v[24:27]
	v_mfma_f32_16x16x32_bf16 v[20:23], v[188:191], v[220:223], v[20:23]
	v_mfma_f32_16x16x32_bf16 v[16:19], v[196:199], v[220:223], v[16:19]
	v_mfma_f32_16x16x32_bf16 v[4:7], v[188:191], v[228:231], v[4:7]
	v_mfma_f32_16x16x32_bf16 v[0:3], v[196:199], v[228:231], v[0:3]
	s_setprio 0
	s_barrier
	s_add_i32 s50, s50, 2
	s_add_u32 vcc_lo, vcc_lo, 0x100
	s_addc_u32 vcc_hi, vcc_hi, 0
	s_add_u32 s12, s12, 0x100
	s_addc_u32 s13, s13, 0

; #define PG8_STAGE(bufoff, gbase, voff) do { _Pragma("unroll") for (int _i = 0; _i < 2; ++_i) \
;         __builtin_amdgcn_global_load_lds((const unsigned*)((const char*)(gbase) + (voff)[_i]), (PG8_LAS unsigned*)(lds + (bufoff) + ldsw + _i * 8192), 16, 0, 0); } while (0)
; #define PG8_LDA(dst, b, h) do { _Pragma("unroll") for (int m = 0; m < 4; ++m) _Pragma("unroll") for (int k = 0; k < 2; ++k) dst[m][k] = *(const PG8_LAS bf16x8*)(lds + PG8_SA(b, h) + aoff + m * 2048 + k * 1024); } while (0)
; #define PG8_LDB(dst, b, h) do { _Pragma("unroll") for (int n = 0; n < 2; ++n) _Pragma("unroll") for (int k = 0; k < 2; ++k) dst[n][k] = *(const PG8_LAS bf16x8*)(lds + PG8_SB(b, h) + boff + n * 2048 + k * 1024); } while (0)
; #define PG8_WAIT_V(n) asm volatile("s_waitcnt vmcnt(" #n ")" ::: "memory")
; #define PG8_BAR __builtin_amdgcn_s_barrier()
; template <class Epi, class Sched, bool ALIGN_EPI = false, bool SP2 = false>
; __device__ __forceinline__ void gemm_phase(PG8_LAS unsigned char* lds, const Gemm g, const Sched& S, const Epi& E) {
;     ...
;     f32x4 acc[2][2][4][2];
; #pragma unroll
;     for (int a = 0; a < 2; ++a)
; #pragma unroll
;         for (int b = 0; b < 2; ++b)
; #pragma unroll
;             for (int m = 0; m < 4; ++m)
; #pragma unroll
;                 for (int n = 0; n < 2; ++n) acc[a][b][m][n] = (f32x4){0.f, 0.f, 0.f, 0.f};
;     ...
;             PG8_LDB(B0, 0, 0); PG8_LDB(B1, 0, 1); PG8_SCHED; PG8_LDA(At, 0, 0); PG8_STAGE(PG8_SA(1, 1), a1 + hstepA, voffA);
;             PG8_WAIT_V(8); PG8_WAIT_L(0); PG8_BAR; PG8_MMA(0, 0, At, B0); PG8_MMA(0, 1, At, B1); PG8_BAR; PG8_SCHED;
;             PG8_LDA(At, 0, 1); PG8_STAGE(PG8_SB(0, 0), b2, voffB); PG8_STAGE(PG8_SB(0, 1), b2 + hstepB, voffB); PG8_STAGE(PG8_SA(0, 0), a2, voffA);
;             PG8_WAIT_V(8); PG8_WAIT_L(0); PG8_BAR; PG8_MMA(1, 0, At, B0); PG8_MMA(1, 1, At, B1); PG8_BAR; PG8_SCHED;
;             PG8_LDB(B0, 1, 0); PG8_LDB(B1, 1, 1); PG8_SCHED; PG8_LDA(At, 1, 0); PG8_STAGE(PG8_SA(0, 1), a2 + hstepA, voffA);
;             PG8_WAIT_V(8); PG8_WAIT_L(0); PG8_BAR; PG8_MMA(0, 0, At, B0); PG8_MMA(0, 1, At, B1); PG8_BAR; PG8_SCHED;
;             PG8_LDA(At, 1, 1); PG8_STAGE(PG8_SB(1, 0), b3, voffB); PG8_STAGE(PG8_SB(1, 1), b3 + hstepB, voffB); PG8_STAGE(PG8_SA(1, 0), a3, voffA);
;             PG8_WAIT_V(8); PG8_WAIT_L(0); PG8_BAR; PG8_MMA(1, 0, At, B0); PG8_MMA(1, 1, At, B1); PG8_BAR; PG8_SCHED;
.LBB0_393:
	s_add_u32 s85, s72, 0x100
	s_addc_u32 s86, s73, 0
	s_add_u32 s10, s74, 0x80
	s_addc_u32 s11, s75, 0
	s_mov_b32 s50, 0
	s_add_i32 s51, s50, 2
	s_add_u32 s72, s10, 0x80
	s_addc_u32 s73, s11, 0
	s_add_i32 s87, 0, 0x10000
	s_cmp_eq_u32 s76, s50
	s_cselect_b32 s73, s69, s73
	s_cselect_b32 s72, s68, s72
	v_add_u32_e32 v142, s87, v147
	s_cselect_b32 s75, s71, s86
	s_cselect_b32 s74, s70, s85
	s_add_i32 s50, 0, 0x14000
	ds_read_b128 v[138:141], v142
	ds_read_b128 v[150:153], v142 offset:1024
	ds_read_b128 v[154:157], v142 offset:2048
	ds_read_b128 v[158:161], v142 offset:3072
	v_add_u32_e32 v142, s50, v147
	ds_read_b128 v[188:191], v142
	ds_read_b128 v[192:195], v142 offset:1024
	ds_read_b128 v[196:199], v142 offset:2048
	ds_read_b128 v[200:203], v142 offset:3072
	v_lshl_add_u64 v[142:143], s[10:11], 0, v[136:137]
	s_add_i32 m0, s17, 0xc000
	ds_read_b128 v[204:207], v149
	ds_read_b128 v[208:211], v149 offset:1024
	ds_read_b128 v[212:215], v149 offset:2048
	ds_read_b128 v[216:219], v149 offset:3072
	ds_read_b128 v[220:223], v149 offset:4096
	ds_read_b128 v[224:227], v149 offset:5120
	ds_read_b128 v[228:231], v149 offset:6144
	ds_read_b128 v[232:235], v149 offset:7168
	global_load_lds_dwordx4 v[142:143], off
	v_lshl_add_u64 v[142:143], s[10:11], 0, v[134:135]
	s_add_i32 m0, s17, 0xe000
	s_nop 0
	global_load_lds_dwordx4 v[142:143], off
	s_waitcnt vmcnt(8)
	s_waitcnt lgkmcnt(0)
	s_barrier
	s_setprio 1
	s_waitcnt lgkmcnt(0)
	v_mfma_f32_16x16x32_bf16 v[124:127], v[138:141], v[204:207], 0
	v_mfma_f32_16x16x32_bf16 v[120:123], v[154:157], v[204:207], 0
	v_mfma_f32_16x16x32_bf16 v[108:111], v[138:141], v[212:215], 0
	v_mfma_f32_16x16x32_bf16 v[104:107], v[154:157], v[212:215], 0
	v_mfma_f32_16x16x32_bf16 v[92:95], v[138:141], v[220:223], 0
	v_mfma_f32_16x16x32_bf16 v[88:91], v[154:157], v[220:223], 0
	v_mfma_f32_16x16x32_bf16 v[76:79], v[138:141], v[228:231], 0
	v_mfma_f32_16x16x32_bf16 v[72:75], v[154:157], v[228:231], 0
	v_mfma_f32_16x16x32_bf16 v[124:127], v[150:153], v[208:211], v[124:127]
	v_mfma_f32_16x16x32_bf16 v[120:123], v[158:161], v[208:211], v[120:123]
	v_mfma_f32_16x16x32_bf16 v[108:111], v[150:153], v[216:219], v[108:111]
	v_mfma_f32_16x16x32_bf16 v[104:107], v[158:161], v[216:219], v[104:107]
	v_mfma_f32_16x16x32_bf16 v[92:95], v[150:153], v[224:227], v[92:95]
	v_mfma_f32_16x16x32_bf16 v[88:91], v[158:161], v[224:227], v[88:91]
	v_mfma_f32_16x16x32_bf16 v[76:79], v[150:153], v[232:235], v[76:79]
	v_mfma_f32_16x16x32_bf16 v[72:75], v[158:161], v[232:235], v[72:75]
	s_setprio 0
	s_setprio 1
	v_mfma_f32_16x16x32_bf16 v[116:119], v[188:191], v[204:207], 0
	v_mfma_f32_16x16x32_bf16 v[112:115], v[196:199], v[204:207], 0
	v_mfma_f32_16x16x32_bf16 v[100:103], v[188:191], v[212:215], 0
	v_mfma_f32_16x16x32_bf16 v[96:99], v[196:199], v[212:215], 0
	v_mfma_f32_16x16x32_bf16 v[84:87], v[188:191], v[220:223], 0
	v_mfma_f32_16x16x32_bf16 v[80:83], v[196:199], v[220:223], 0
	v_mfma_f32_16x16x32_bf16 v[68:71], v[188:191], v[228:231], 0
	v_mfma_f32_16x16x32_bf16 v[64:67], v[196:199], v[228:231], 0
	v_mfma_f32_16x16x32_bf16 v[116:119], v[192:195], v[208:211], v[116:119]
	v_mfma_f32_16x16x32_bf16 v[112:115], v[200:203], v[208:211], v[112:115]
	v_mfma_f32_16x16x32_bf16 v[100:103], v[192:195], v[216:219], v[100:103]
	v_mfma_f32_16x16x32_bf16 v[96:99], v[200:203], v[216:219], v[96:99]
	v_mfma_f32_16x16x32_bf16 v[84:87], v[192:195], v[224:227], v[84:87]
	v_mfma_f32_16x16x32_bf16 v[80:83], v[200:203], v[224:227], v[80:83]
	v_mfma_f32_16x16x32_bf16 v[68:71], v[192:195], v[232:235], v[68:71]
	v_mfma_f32_16x16x32_bf16 v[64:67], v[200:203], v[232:235], v[64:67]
	s_setprio 0
	s_barrier
	s_add_i32 s87, s87, s16
	v_lshl_add_u64 v[142:143], s[74:75], 0, v[144:145]
	s_mov_b32 m0, s87
	ds_read_b128 v[204:207], v149 offset:16384
	ds_read_b128 v[208:211], v149 offset:17408
	ds_read_b128 v[212:215], v149 offset:18432
	ds_read_b128 v[216:219], v149 offset:19456
	ds_read_b128 v[220:223], v149 offset:20480
	ds_read_b128 v[224:227], v149 offset:21504
	ds_read_b128 v[228:231], v149 offset:22528
	ds_read_b128 v[232:235], v149 offset:23552
	global_load_lds_dwordx4 v[142:143], off
	s_add_i32 m0, s87, 0x2000
	v_lshl_add_u64 v[174:175], s[74:75], 0, v[132:133]
	s_add_u32 s74, s74, s6
	s_addc_u32 s75, s75, 0
	s_add_i32 s50, s50, s16
	global_load_lds_dwordx4 v[174:175], off
	v_lshl_add_u64 v[236:237], s[74:75], 0, v[144:145]
	s_mov_b32 m0, s50
	v_lshl_add_u64 v[238:239], s[74:75], 0, v[132:133]
	global_load_lds_dwordx4 v[236:237], off
	s_add_i32 m0, s50, 0x2000
	v_lshl_add_u64 v[240:241], s[72:73], 0, v[128:129]
	global_load_lds_dwordx4 v[238:239], off
	s_mov_b32 m0, s17
	v_lshl_add_u64 v[242:243], s[72:73], 0, v[130:131]
	global_load_lds_dwordx4 v[240:241], off
	s_mov_b32 m0, s18
	s_nop 0
	global_load_lds_dwordx4 v[242:243], off
	s_waitcnt vmcnt(8)
	s_waitcnt lgkmcnt(0)
	s_barrier
; #define PG8_STAGE(bufoff, gbase, voff) do { _Pragma("unroll") for (int _i = 0; _i < 2; ++_i) \
;         __builtin_amdgcn_global_load_lds((const unsigned*)((const char*)(gbase) + (voff)[_i]), (PG8_LAS unsigned*)(lds + (bufoff) + ldsw + _i * 8192), 16, 0, 0); } while (0)
; #define PG8_LDA(dst, b, h) do { _Pragma("unroll") for (int m = 0; m < 4; ++m) _Pragma("unroll") for (int k = 0; k < 2; ++k) dst[m][k] = *(const PG8_LAS bf16x8*)(lds + PG8_SA(b, h) + aoff + m * 2048 + k * 1024); } while (0)
; #define PG8_LDB(dst, b, h) do { _Pragma("unroll") for (int n = 0; n < 2; ++n) _Pragma("unroll") for (int k = 0; k < 2; ++k) dst[n][k] = *(const PG8_LAS bf16x8*)(lds + PG8_SB(b, h) + boff + n * 2048 + k * 1024); } while (0)
; #define PG8_MMA(ai, bj, At, Bt) do { __builtin_amdgcn_s_setprio(1); _Pragma("unroll") for (int m = 0; m < 4; ++m) _Pragma("unroll") for (int n = 0; n < 2; ++n) _Pragma("unroll") for (int k = 0; k < 2; ++k) \
;         acc[ai][bj][m][n] = __builtin_amdgcn_mfma_f32_16x16x32_bf16(Bt[n][k], At[m][k], acc[ai][bj][m][n], 0, 0, 0); __builtin_amdgcn_s_setprio(0); } while (0)
; #define PG8_WAIT_V(n) asm volatile("s_waitcnt vmcnt(" #n ")" ::: "memory")
; #define PG8_WAIT_L(n) asm volatile("s_waitcnt lgkmcnt(" #n ")" ::: "memory")
; #define PG8_BAR __builtin_amdgcn_s_barrier()
; #define PG8_SCHED __builtin_amdgcn_sched_barrier(0)
; template <class Epi, class Sched, bool ALIGN_EPI = false, bool SP2 = false>
; __device__ __forceinline__ void gemm_phase(PG8_LAS unsigned char* lds, const Gemm g, const Sched& S, const Epi& E) {
;     ...
;             PG8_LDA(At, 0, 1); PG8_STAGE(PG8_SB(0, 0), b2, voffB); PG8_STAGE(PG8_SB(0, 1), b2 + hstepB, voffB); PG8_STAGE(PG8_SA(0, 0), a2, voffA);
;             PG8_WAIT_V(8); PG8_WAIT_L(0); PG8_BAR; PG8_MMA(1, 0, At, B0); PG8_MMA(1, 1, At, B1); PG8_BAR; PG8_SCHED;
;             PG8_LDB(B0, 1, 0); PG8_LDB(B1, 1, 1); PG8_SCHED; PG8_LDA(At, 1, 0); PG8_STAGE(PG8_SA(0, 1), a2 + hstepA, voffA);
;             PG8_WAIT_V(8); PG8_WAIT_L(0); PG8_BAR; PG8_MMA(0, 0, At, B0); PG8_MMA(0, 1, At, B1); PG8_BAR; PG8_SCHED;
	s_setprio 1
	s_waitcnt lgkmcnt(0)
	v_mfma_f32_16x16x32_bf16 v[60:63], v[138:141], v[204:207], 0
	v_mfma_f32_16x16x32_bf16 v[56:59], v[154:157], v[204:207], 0
	v_mfma_f32_16x16x32_bf16 v[44:47], v[138:141], v[212:215], 0
	v_mfma_f32_16x16x32_bf16 v[40:43], v[154:157], v[212:215], 0
	v_mfma_f32_16x16x32_bf16 v[28:31], v[138:141], v[220:223], 0
	v_mfma_f32_16x16x32_bf16 v[24:27], v[154:157], v[220:223], 0
	v_mfma_f32_16x16x32_bf16 v[12:15], v[138:141], v[228:231], 0
	v_mfma_f32_16x16x32_bf16 v[8:11], v[154:157], v[228:231], 0
	v_mfma_f32_16x16x32_bf16 v[60:63], v[150:153], v[208:211], v[60:63]
	v_mfma_f32_16x16x32_bf16 v[56:59], v[158:161], v[208:211], v[56:59]
	v_mfma_f32_16x16x32_bf16 v[44:47], v[150:153], v[216:219], v[44:47]
	v_mfma_f32_16x16x32_bf16 v[40:43], v[158:161], v[216:219], v[40:43]
	v_mfma_f32_16x16x32_bf16 v[28:31], v[150:153], v[224:227], v[28:31]
	v_mfma_f32_16x16x32_bf16 v[24:27], v[158:161], v[224:227], v[24:27]
	v_mfma_f32_16x16x32_bf16 v[12:15], v[150:153], v[232:235], v[12:15]
	v_mfma_f32_16x16x32_bf16 v[8:11], v[158:161], v[232:235], v[8:11]
	s_setprio 0
	s_setprio 1
	v_mfma_f32_16x16x32_bf16 v[52:55], v[188:191], v[204:207], 0
	v_mfma_f32_16x16x32_bf16 v[48:51], v[196:199], v[204:207], 0
	v_mfma_f32_16x16x32_bf16 v[36:39], v[188:191], v[212:215], 0
	v_mfma_f32_16x16x32_bf16 v[32:35], v[196:199], v[212:215], 0
	v_mfma_f32_16x16x32_bf16 v[20:23], v[188:191], v[220:223], 0
	v_mfma_f32_16x16x32_bf16 v[16:19], v[196:199], v[220:223], 0
	v_mfma_f32_16x16x32_bf16 v[4:7], v[188:191], v[228:231], 0
	v_mfma_f32_16x16x32_bf16 v[0:3], v[196:199], v[228:231], 0
	v_mfma_f32_16x16x32_bf16 v[52:55], v[192:195], v[208:211], v[52:55]
	v_mfma_f32_16x16x32_bf16 v[48:51], v[200:203], v[208:211], v[48:51]
	v_mfma_f32_16x16x32_bf16 v[36:39], v[192:195], v[216:219], v[36:39]
	v_mfma_f32_16x16x32_bf16 v[32:35], v[200:203], v[216:219], v[32:35]
	v_mfma_f32_16x16x32_bf16 v[20:23], v[192:195], v[224:227], v[20:23]
	v_mfma_f32_16x16x32_bf16 v[16:19], v[200:203], v[224:227], v[16:19]
	v_mfma_f32_16x16x32_bf16 v[4:7], v[192:195], v[232:235], v[4:7]
	v_mfma_f32_16x16x32_bf16 v[0:3], v[200:203], v[232:235], v[0:3]
	s_setprio 0
	s_barrier
	s_add_i32 s50, 0, 0x18000
	s_add_i32 s74, 0, 0x1c000
	v_add_u32_e32 v158, s50, v147
	v_add_u32_e32 v162, s74, v147
	ds_read_b128 v[138:141], v158
	ds_read_b128 v[150:153], v158 offset:1024
	ds_read_b128 v[154:157], v158 offset:2048
	ds_read_b128 v[158:161], v158 offset:3072
	ds_read_b128 v[188:191], v162
	ds_read_b128 v[192:195], v162 offset:1024
	ds_read_b128 v[196:199], v162 offset:2048
	ds_read_b128 v[200:203], v162 offset:3072
	s_add_u32 s72, s72, s34
	s_addc_u32 s73, s73, 0
	s_mov_b32 m0, s19
	v_lshl_add_u64 v[244:245], s[72:73], 0, v[128:129]
	ds_read_b128 v[204:207], v149 offset:32768
	ds_read_b128 v[208:211], v149 offset:33792
	ds_read_b128 v[212:215], v149 offset:34816
	ds_read_b128 v[216:219], v149 offset:35840
	ds_read_b128 v[220:223], v149 offset:36864
	ds_read_b128 v[224:227], v149 offset:37888
	ds_read_b128 v[228:231], v149 offset:38912
	ds_read_b128 v[232:235], v149 offset:39936
	global_load_lds_dwordx4 v[244:245], off
	v_lshl_add_u64 v[244:245], s[72:73], 0, v[130:131]
	s_mov_b32 m0, s24
	s_nop 0
	global_load_lds_dwordx4 v[244:245], off
	s_waitcnt vmcnt(8)
	s_waitcnt lgkmcnt(0)
	s_barrier
	s_setprio 1
	s_waitcnt lgkmcnt(0)
	v_mfma_f32_16x16x32_bf16 v[124:127], v[138:141], v[204:207], v[124:127]
	v_mfma_f32_16x16x32_bf16 v[120:123], v[154:157], v[204:207], v[120:123]
	v_mfma_f32_16x16x32_bf16 v[108:111], v[138:141], v[212:215], v[108:111]
	v_mfma_f32_16x16x32_bf16 v[104:107], v[154:157], v[212:215], v[104:107]
	v_mfma_f32_16x16x32_bf16 v[92:95], v[138:141], v[220:223], v[92:95]
	v_mfma_f32_16x16x32_bf16 v[88:91], v[154:157], v[220:223], v[88:91]
	v_mfma_f32_16x16x32_bf16 v[76:79], v[138:141], v[228:231], v[76:79]
	v_mfma_f32_16x16x32_bf16 v[72:75], v[154:157], v[228:231], v[72:75]
	v_mfma_f32_16x16x32_bf16 v[124:127], v[150:153], v[208:211], v[124:127]
	v_mfma_f32_16x16x32_bf16 v[120:123], v[158:161], v[208:211], v[120:123]
	v_mfma_f32_16x16x32_bf16 v[108:111], v[150:153], v[216:219], v[108:111]
	v_mfma_f32_16x16x32_bf16 v[104:107], v[158:161], v[216:219], v[104:107]
	v_mfma_f32_16x16x32_bf16 v[92:95], v[150:153], v[224:227], v[92:95]
	v_mfma_f32_16x16x32_bf16 v[88:91], v[158:161], v[224:227], v[88:91]
	v_mfma_f32_16x16x32_bf16 v[76:79], v[150:153], v[232:235], v[76:79]
	v_mfma_f32_16x16x32_bf16 v[72:75], v[158:161], v[232:235], v[72:75]
	s_setprio 0
	s_setprio 1
	v_mfma_f32_16x16x32_bf16 v[116:119], v[188:191], v[204:207], v[116:119]
	v_mfma_f32_16x16x32_bf16 v[112:115], v[196:199], v[204:207], v[112:115]
	v_mfma_f32_16x16x32_bf16 v[100:103], v[188:191], v[212:215], v[100:103]
	v_mfma_f32_16x16x32_bf16 v[96:99], v[196:199], v[212:215], v[96:99]
	v_mfma_f32_16x16x32_bf16 v[84:87], v[188:191], v[220:223], v[84:87]
	v_mfma_f32_16x16x32_bf16 v[80:83], v[196:199], v[220:223], v[80:83]
	v_mfma_f32_16x16x32_bf16 v[68:71], v[188:191], v[228:231], v[68:71]
	v_mfma_f32_16x16x32_bf16 v[64:67], v[196:199], v[228:231], v[64:67]
	v_mfma_f32_16x16x32_bf16 v[116:119], v[192:195], v[208:211], v[116:119]
	v_mfma_f32_16x16x32_bf16 v[112:115], v[200:203], v[208:211], v[112:115]
	v_mfma_f32_16x16x32_bf16 v[100:103], v[192:195], v[216:219], v[100:103]
	v_mfma_f32_16x16x32_bf16 v[96:99], v[200:203], v[216:219], v[96:99]
	v_mfma_f32_16x16x32_bf16 v[84:87], v[192:195], v[224:227], v[84:87]
	v_mfma_f32_16x16x32_bf16 v[80:83], v[200:203], v[224:227], v[80:83]
	v_mfma_f32_16x16x32_bf16 v[68:71], v[192:195], v[232:235], v[68:71]
	v_mfma_f32_16x16x32_bf16 v[64:67], v[200:203], v[232:235], v[64:67]
	s_setprio 0
	s_barrier
; #define PG8_STAGE(bufoff, gbase, voff) do { _Pragma("unroll") for (int _i = 0; _i < 2; ++_i) \
;         __builtin_amdgcn_global_load_lds((const unsigned*)((const char*)(gbase) + (voff)[_i]), (PG8_LAS unsigned*)(lds + (bufoff) + ldsw + _i * 8192), 16, 0, 0); } while (0)
; #define PG8_LDA(dst, b, h) do { _Pragma("unroll") for (int m = 0; m < 4; ++m) _Pragma("unroll") for (int k = 0; k < 2; ++k) dst[m][k] = *(const PG8_LAS bf16x8*)(lds + PG8_SA(b, h) + aoff + m * 2048 + k * 1024); } while (0)
; #define PG8_MMA(ai, bj, At, Bt) do { __builtin_amdgcn_s_setprio(1); _Pragma("unroll") for (int m = 0; m < 4; ++m) _Pragma("unroll") for (int n = 0; n < 2; ++n) _Pragma("unroll") for (int k = 0; k < 2; ++k) \
;         acc[ai][bj][m][n] = __builtin_amdgcn_mfma_f32_16x16x32_bf16(Bt[n][k], At[m][k], acc[ai][bj][m][n], 0, 0, 0); __builtin_amdgcn_s_setprio(0); } while (0)
; #define PG8_WAIT_V(n) asm volatile("s_waitcnt vmcnt(" #n ")" ::: "memory")
; #define PG8_WAIT_L(n) asm volatile("s_waitcnt lgkmcnt(" #n ")" ::: "memory")
; #define PG8_BAR __builtin_amdgcn_s_barrier()
; #define PG8_SCHED __builtin_amdgcn_sched_barrier(0)
; template <class Epi, class Sched, bool ALIGN_EPI = false, bool SP2 = false>
; __device__ __forceinline__ void gemm_phase(PG8_LAS unsigned char* lds, const Gemm g, const Sched& S, const Epi& E) {
;     ...
;             PG8_LDA(At, 1, 1); PG8_STAGE(PG8_SB(1, 0), b3, voffB); PG8_STAGE(PG8_SB(1, 1), b3 + hstepB, voffB); PG8_STAGE(PG8_SA(1, 0), a3, voffA);
;             PG8_WAIT_V(8); PG8_WAIT_L(0); PG8_BAR; PG8_MMA(1, 0, At, B0); PG8_MMA(1, 1, At, B1); PG8_BAR; PG8_SCHED;
	s_add_i32 s50, s50, s16
	v_lshl_add_u64 v[142:143], v[142:143], 0, s[48:49]
	s_mov_b32 m0, s50
	ds_read_b128 v[204:207], v149 offset:49152
	ds_read_b128 v[208:211], v149 offset:50176
	ds_read_b128 v[212:215], v149 offset:51200
	ds_read_b128 v[216:219], v149 offset:52224
	ds_read_b128 v[220:223], v149 offset:53248
	ds_read_b128 v[224:227], v149 offset:54272
	ds_read_b128 v[228:231], v149 offset:55296
	ds_read_b128 v[232:235], v149 offset:56320
	global_load_lds_dwordx4 v[142:143], off
	v_lshl_add_u64 v[142:143], v[174:175], 0, s[48:49]
	s_add_i32 m0, s50, 0x2000
	s_add_i32 s50, s74, s16
	global_load_lds_dwordx4 v[142:143], off
	v_lshl_add_u64 v[142:143], v[236:237], 0, s[48:49]
	s_mov_b32 m0, s50
	s_nop 0
	global_load_lds_dwordx4 v[142:143], off
	v_lshl_add_u64 v[142:143], v[238:239], 0, s[48:49]
	s_add_i32 m0, s50, 0x2000
	s_nop 0
	global_load_lds_dwordx4 v[142:143], off
	v_lshl_add_u64 v[142:143], v[240:241], 0, s[48:49]
	s_mov_b32 m0, s31
	s_nop 0
	global_load_lds_dwordx4 v[142:143], off
	v_lshl_add_u64 v[142:143], v[242:243], 0, s[48:49]
	s_mov_b32 m0, s37
	s_nop 0
	global_load_lds_dwordx4 v[142:143], off
	s_waitcnt vmcnt(8)
	s_waitcnt lgkmcnt(0)
	s_barrier
	s_setprio 1
	s_waitcnt lgkmcnt(0)
	v_mfma_f32_16x16x32_bf16 v[60:63], v[138:141], v[204:207], v[60:63]
	v_mfma_f32_16x16x32_bf16 v[56:59], v[154:157], v[204:207], v[56:59]
	v_mfma_f32_16x16x32_bf16 v[44:47], v[138:141], v[212:215], v[44:47]
	v_mfma_f32_16x16x32_bf16 v[40:43], v[154:157], v[212:215], v[40:43]
	v_mfma_f32_16x16x32_bf16 v[28:31], v[138:141], v[220:223], v[28:31]
	v_mfma_f32_16x16x32_bf16 v[24:27], v[154:157], v[220:223], v[24:27]
	v_mfma_f32_16x16x32_bf16 v[12:15], v[138:141], v[228:231], v[12:15]
	v_mfma_f32_16x16x32_bf16 v[8:11], v[154:157], v[228:231], v[8:11]
	v_mfma_f32_16x16x32_bf16 v[60:63], v[150:153], v[208:211], v[60:63]
	v_mfma_f32_16x16x32_bf16 v[56:59], v[158:161], v[208:211], v[56:59]
	v_mfma_f32_16x16x32_bf16 v[44:47], v[150:153], v[216:219], v[44:47]
	v_mfma_f32_16x16x32_bf16 v[40:43], v[158:161], v[216:219], v[40:43]
	v_mfma_f32_16x16x32_bf16 v[28:31], v[150:153], v[224:227], v[28:31]
	v_mfma_f32_16x16x32_bf16 v[24:27], v[158:161], v[224:227], v[24:27]
	v_mfma_f32_16x16x32_bf16 v[12:15], v[150:153], v[232:235], v[12:15]
	v_mfma_f32_16x16x32_bf16 v[8:11], v[158:161], v[232:235], v[8:11]
	s_setprio 0
	s_setprio 1
	v_mfma_f32_16x16x32_bf16 v[52:55], v[188:191], v[204:207], v[52:55]
	v_mfma_f32_16x16x32_bf16 v[48:51], v[196:199], v[204:207], v[48:51]
	v_mfma_f32_16x16x32_bf16 v[36:39], v[188:191], v[212:215], v[36:39]
	v_mfma_f32_16x16x32_bf16 v[32:35], v[196:199], v[212:215], v[32:35]
	v_mfma_f32_16x16x32_bf16 v[20:23], v[188:191], v[220:223], v[20:23]
	v_mfma_f32_16x16x32_bf16 v[16:19], v[196:199], v[220:223], v[16:19]
	v_mfma_f32_16x16x32_bf16 v[4:7], v[188:191], v[228:231], v[4:7]
	v_mfma_f32_16x16x32_bf16 v[0:3], v[196:199], v[228:231], v[0:3]
	v_mfma_f32_16x16x32_bf16 v[52:55], v[192:195], v[208:211], v[52:55]
	v_mfma_f32_16x16x32_bf16 v[48:51], v[200:203], v[208:211], v[48:51]
	v_mfma_f32_16x16x32_bf16 v[36:39], v[192:195], v[216:219], v[36:39]
	v_mfma_f32_16x16x32_bf16 v[32:35], v[200:203], v[216:219], v[32:35]
	v_mfma_f32_16x16x32_bf16 v[20:23], v[192:195], v[224:227], v[20:23]
	v_mfma_f32_16x16x32_bf16 v[16:19], v[200:203], v[224:227], v[16:19]
	v_mfma_f32_16x16x32_bf16 v[4:7], v[192:195], v[232:235], v[4:7]
	v_mfma_f32_16x16x32_bf16 v[0:3], v[200:203], v[232:235], v[0:3]
	s_setprio 0
	s_barrier
	s_add_u32 s85, s85, 0x100
	s_addc_u32 s86, s86, 0
	s_add_u32 s10, s10, 0x100
	s_addc_u32 s11, s11, 0
	s_mov_b32 s50, s51
